# grid barrier: non-leader workgroups issue the L1 invalidate at arrival (while waiting) instead of after the release
# speedup vs baseline: 1.0025x; 1.0009x over previous
; __device__ __forceinline__ unsigned xb_ld(unsigned* p)              { return __hip_atomic_load(p, __ATOMIC_RELAXED, __HIP_MEMORY_SCOPE_AGENT); }
; __device__ __forceinline__ unsigned xb_add(unsigned* p, unsigned v) { return __hip_atomic_fetch_add(p, v, __ATOMIC_RELAXED, __HIP_MEMORY_SCOPE_AGENT); }
; #define XB_SPIN(cond, bar) do { unsigned _sp = 0; while (cond) { __builtin_amdgcn_s_sleep(1); \
;     if ((++_sp & 255u) == 0u) { if (xb_ld(&(bar)[XB_TMO])) break; if (_sp > XB_SPIN_CAP) { atomicAdd(&(bar)[XB_TMO], 1u); break; } } } } while (0)
; __device__ __forceinline__ void xcd_barrier(const XcdBarrier& b) {
;     ...
;         const unsigned old = xb_add(&bar[XB_XSUB(b.x)], 1u);
;         const unsigned gen = old / nloc;
;         if (old + 1u == (gen + 1u) * nloc) {
;             __builtin_amdgcn_fence(__ATOMIC_RELEASE, "agent");
;             asm volatile("s_waitcnt vmcnt(0)" ::: "memory");
;             const unsigned og = xb_add(&bar[XB_TOP], 1u);
;             const unsigned tg = og / nx;
;             if (og + 1u == (tg + 1u) * nx) xb_add(&bar[XB_TOPGEN], 1u);
;             else XB_SPIN(xb_ld(&bar[XB_TOPGEN]) == tg, bar);
;             __builtin_amdgcn_fence(__ATOMIC_ACQUIRE, "agent");
;             xb_add(&bar[XB_XGEN(b.x)], 1u);
;             asm volatile("s_waitcnt vmcnt(0)" ::: "memory");
;         } else {
;             XB_SPIN(xb_ld(&bar[XB_XGEN(b.x)]) == gen, bar);
.LBB0_849:
	v_readlane_b32 s2, v254, 42
	v_readlane_b32 s3, v254, 43
	v_readlane_b32 s2, v254, 41
	s_mov_b32 s7, s3
	s_lshl_b32 s6, s2, 6
	v_writelane_b32 v254, s2, 42
	v_mov_b32_e32 v1, 0x1000
	v_sub_u32_e32 v4, 0, v2
	v_writelane_b32 v254, s3, 43
	s_lshl_b64 s[2:3], s[6:7], 2
	v_readlane_b32 s6, v252, 2
	v_readlane_b32 s7, v252, 3
	s_add_u32 s6, s6, s2
	s_addc_u32 s7, s7, s3
	s_nop 2
	global_atomic_add v3, v1, v183, s[6:7] offset:1024 sc0
	v_cvt_f32_u32_e32 v1, v2
	v_rcp_iflag_f32_e32 v1, v1
	s_nop 0
	v_mul_f32_e32 v1, 0x4f7ffffe, v1
	v_cvt_u32_f32_e32 v1, v1
	v_mul_lo_u32 v4, v4, v1
	v_mul_hi_u32 v4, v1, v4
	v_add_u32_e32 v1, v1, v4
	s_waitcnt vmcnt(0)
	v_mul_hi_u32 v1, v3, v1
	v_mul_lo_u32 v4, v1, v2
	v_sub_u32_e32 v4, v3, v4
	v_add_u32_e32 v5, 1, v1
	v_cmp_ge_u32_e32 vcc, v4, v2
	v_add_u32_e32 v3, 1, v3
	s_nop 0
	v_cndmask_b32_e32 v1, v1, v5, vcc
	v_sub_u32_e32 v5, v4, v2
	v_cndmask_b32_e32 v4, v4, v5, vcc
	v_add_u32_e32 v5, 1, v1
	v_cmp_ge_u32_e32 vcc, v4, v2
	s_nop 1
	v_cndmask_b32_e32 v1, v1, v5, vcc
	v_mul_lo_u32 v4, v2, v1
	v_add_u32_e32 v2, v4, v2
	v_cmp_ne_u32_e32 vcc, v3, v2
	s_and_saveexec_b64 s[2:3], vcc
	s_xor_b64 s[8:9], exec, s[2:3]
	s_cbranch_execz .LBB0_863
	buffer_inv sc1
	s_waitcnt lgkmcnt(0)
	v_mov_b32_e32 v0, 0x2000
	global_load_dword v0, v0, s[6:7] offset:1024 sc1
	s_add_u32 s12, s6, 0x2400
	s_addc_u32 s13, s7, 0
	s_waitcnt vmcnt(0)
	v_cmp_eq_u32_e32 vcc, v0, v1
	s_and_saveexec_b64 s[10:11], vcc
	s_cbranch_execz .LBB0_862
	s_mov_b32 s2, 1
	s_mov_b64 s[14:15], 0
	s_branch .LBB0_853

; __device__ __forceinline__ unsigned xb_ld(unsigned* p)              { return __hip_atomic_load(p, __ATOMIC_RELAXED, __HIP_MEMORY_SCOPE_AGENT); }
; #define XB_SPIN(cond, bar) do { unsigned _sp = 0; while (cond) { __builtin_amdgcn_s_sleep(1); \
;     if ((++_sp & 255u) == 0u) { if (xb_ld(&(bar)[XB_TMO])) break; if (_sp > XB_SPIN_CAP) { atomicAdd(&(bar)[XB_TMO], 1u); break; } } } } while (0)
; __device__ __forceinline__ void xcd_barrier(const XcdBarrier& b) {
;     ...
;             XB_SPIN(xb_ld(&bar[XB_XGEN(b.x)]) == gen, bar);
;             __builtin_amdgcn_fence(__ATOMIC_ACQUIRE, "agent");
;             asm volatile("s_waitcnt vmcnt(0)" ::: "memory");
.LBB0_862:
	s_or_b64 exec, exec, s[10:11]
	s_waitcnt vmcnt(0)
	s_waitcnt vmcnt(0)
